# hgrn2 chunk loop: cvt_pk packing instead of integer RNE trick, one 64-bit base per prefetch row (fewer VALU per chunk)
# baseline (speedup 1.0000x reference)
; __device__ __forceinline__ unsigned cvt_pk_bf16(float lo, float hi) { unsigned r; asm volatile("v_cvt_pk_bf16_f32 %0, %1, %2" : "=v"(r) : "v"(lo), "v"(hi)); return r; }
; DI unsigned pk2(float lo, float hi) { return f2bf(lo) | (f2bf(hi) << 16); }
; DI float lo_f(unsigned w) { return __uint_as_float(w << 16); }
; DI float hi_f(unsigned w) { return __uint_as_float(w & 0xffff0000u); }
; DI void hgrn2_block(const Args& a, unsigned char* lds, int bh, int tid, int wave, int lane) {
;     ...
;         { const int t = 32 * tc + r; const f32x4 q4 = *(const f32x4*)(rss + t * 4);
;           const float rs = rsqrtf((q4[0] + q4[1] + q4[2] + q4[3]) * (1.f / 128.f) + EPS);
;           bf16_t* Ost = Qt;
; #pragma unroll
;           for (int g = 0; g < 4; ++g) { u32x2 w; w.x = pk2(oacc[4 * g] * rs, oacc[4 * g + 1] * rs); w.y = pk2(oacc[4 * g + 2] * rs, oacc[4 * g + 3] * rs); *(u32x2*)(Ost + t * 136 + 32 * vt + 8 * g + 4 * hh) = w; }
; #pragma unroll
;           for (int g = 0; g < 4; ++g) { u32x2 w0, w1; w0.x = pk2(S0[4 * g], S0[4 * g + 1]); w0.y = pk2(S0[4 * g + 2], S0[4 * g + 3]); w1.x = pk2(S1[4 * g], S1[4 * g + 1]); w1.y = pk2(S1[4 * g + 2], S1[4 * g + 3]);
;               *(u32x2*)(ST + (32 * vt2 + r) * 136 + 32 * ct + 8 * g + 4 * hh) = w0; *(u32x2*)(ST + (32 * (vt2 + 1) + r) * 136 + 32 * ct + 8 * g + 4 * hh) = w1; } }
;         __syncthreads();
;         { const int t = tid >> 3, v0 = (tid & 7) * 16; const size_t grow = (size_t)(tok0 + 64 * c + t);
;           const u32x4* os = (const u32x4*)(Qt + t * 136 + v0);
;           u32x4* dst = (u32x4*)(AB + grow * D_ + 1024 + h * 128 + v0);
; #pragma unroll
;           for (int q = 0; q < 2; ++q) { const u32x4 ow = os[q], gw4 = hgc[q]; const float* gp = gn + v0 + 8 * q;
;               u32x4 w;
;               w.x = pg8::cvt_pk_bf16(lo_f(ow.x) * gp[0] * lo_f(gw4.x), hi_f(ow.x) * gp[1] * hi_f(gw4.x));
;               w.y = pg8::cvt_pk_bf16(lo_f(ow.y) * gp[2] * lo_f(gw4.y), hi_f(ow.y) * gp[3] * hi_f(gw4.y));
;               w.z = pg8::cvt_pk_bf16(lo_f(ow.z) * gp[4] * lo_f(gw4.z), hi_f(ow.z) * gp[5] * hi_f(gw4.z));
;               w.w = pg8::cvt_pk_bf16(lo_f(ow.w) * gp[6] * lo_f(gw4.w), hi_f(ow.w) * gp[7] * hi_f(gw4.w));
;               dst[q] = w; } }
.LBB0_226:
	s_or_b64 exec, exec, s[68:69]
	s_waitcnt lgkmcnt(0)
	s_barrier
	ds_read_b128 v[150:153], v104
	s_mov_b32 s68, 0x800000
	s_waitcnt vmcnt(8)
	v_mov_b32_e32 v163, v144
	v_mov_b32_e32 v161, v142
	s_waitcnt vmcnt(5)
	v_mov_b32_e32 v159, v146
	s_waitcnt lgkmcnt(0)
	v_add_f32_e32 v150, v150, v151
	v_add_f32_e32 v150, v152, v150
	v_add_f32_e32 v150, v153, v150
	v_fmamk_f32 v150, v150, 0x3c000000, v105
	v_cmp_gt_f32_e32 vcc, s68, v150
	v_mul_f32_e32 v151, 0x4b800000, v150
	s_nop 0
	v_cndmask_b32_e32 v150, v150, v151, vcc
	v_rsq_f32_e32 v150, v150
	s_nop 0
	s_nop 0
	s_mov_b64 s[68:69], 0x24dcc800
	v_mul_f32_e32 v151, 0x45800000, v150
	v_cndmask_b32_e32 v150, v150, v151, vcc
	v_pk_mul_f32 v[34:35], v[34:35], v[150:151] op_sel_hi:[1,0]
	v_pk_mul_f32 v[36:37], v[36:37], v[150:151] op_sel_hi:[1,0]
	v_pk_mul_f32 v[38:39], v[38:39], v[150:151] op_sel_hi:[1,0]
	v_pk_mul_f32 v[40:41], v[40:41], v[150:151] op_sel_hi:[1,0]
	v_pk_mul_f32 v[42:43], v[42:43], v[150:151] op_sel_hi:[1,0]
	v_pk_mul_f32 v[44:45], v[44:45], v[150:151] op_sel_hi:[1,0]
	v_pk_mul_f32 v[46:47], v[46:47], v[150:151] op_sel_hi:[1,0]
	v_pk_mul_f32 v[48:49], v[48:49], v[150:151] op_sel_hi:[1,0]
	v_cvt_pk_bf16_f32 v34, v34, v35
	v_cvt_pk_bf16_f32 v35, v36, v37
	v_cvt_pk_bf16_f32 v36, v38, v39
	v_cvt_pk_bf16_f32 v37, v40, v41
	v_cvt_pk_bf16_f32 v38, v42, v43
	v_cvt_pk_bf16_f32 v39, v44, v45
	v_cvt_pk_bf16_f32 v40, v46, v47
	v_cvt_pk_bf16_f32 v41, v48, v49
	ds_write2_b64 v106, v[34:35], v[36:37] offset1:2
	ds_write2_b64 v106, v[38:39], v[40:41] offset0:4 offset1:6
	v_cvt_pk_bf16_f32 v42, v2, v3
	v_cvt_pk_bf16_f32 v43, v4, v5
	v_cvt_pk_bf16_f32 v44, v18, v19
	v_cvt_pk_bf16_f32 v45, v20, v21
	ds_write_b64 v98, v[42:43]
	ds_write_b64 v99, v[44:45]
	v_cvt_pk_bf16_f32 v46, v6, v7
	v_cvt_pk_bf16_f32 v47, v8, v9
	v_cvt_pk_bf16_f32 v48, v22, v23
	v_cvt_pk_bf16_f32 v49, v24, v25
	ds_write_b64 v98, v[46:47] offset:16
	ds_write_b64 v99, v[48:49] offset:16
	v_cvt_pk_bf16_f32 v42, v10, v11
	v_cvt_pk_bf16_f32 v43, v12, v13
	v_cvt_pk_bf16_f32 v44, v26, v27
	v_cvt_pk_bf16_f32 v45, v28, v29
	ds_write_b64 v98, v[42:43] offset:32
	ds_write_b64 v99, v[44:45] offset:32
	v_cvt_pk_bf16_f32 v46, v14, v15
	v_cvt_pk_bf16_f32 v47, v16, v17
	v_cvt_pk_bf16_f32 v48, v30, v31
	v_cvt_pk_bf16_f32 v49, v32, v33
	ds_write_b64 v98, v[46:47] offset:48
	ds_write_b64 v99, v[48:49] offset:48
	s_waitcnt lgkmcnt(0)
	s_barrier
	ds_read_b128 v[36:39], v107
	v_add_u32_e32 v34, s87, v78
	v_ashrrev_i32_e32 v35, 31, v34
	v_lshlrev_b64 v[34:35], 12, v[34:35]
	v_lshl_add_u64 v[34:35], s[84:85], 0, v[34:35]
	s_waitcnt lgkmcnt(0)
	v_lshlrev_b32_e32 v44, 16, v36
	v_and_b32_e32 v36, 0xffff0000, v36
	v_lshl_add_u64 v[34:35], v[34:35], 0, s[92:93]
	v_lshl_add_u64 v[40:41], v[34:35], 0, v[66:67]
	v_lshl_add_u64 v[34:35], v[40:41], 0, s[68:69]
	s_mov_b32 s68, 0x24dcc000
	v_add_co_u32_e32 v40, vcc, s68, v40
	s_add_i32 s87, s87, 64
	s_nop 0
	v_addc_co_u32_e32 v41, vcc, 0, v41, vcc
	s_cmpk_lg_i32 s87, 0x800
	v_mov_b32_e32 v150, v140
	v_mov_b32_e32 v49, v138
	v_mov_b32_e32 v152, v136
	v_mov_b32_e32 v151, v134
	v_mov_b32_e32 v46, v133
	v_mov_b32_e32 v45, v130
	v_mov_b32_e32 v48, v128
	v_mov_b32_e32 v47, v125
	s_waitcnt vmcnt(2)
	v_mov_b32_e32 v164, v149
	v_mov_b32_e32 v157, v124
	v_mov_b32_e32 v158, v129
	v_mov_b32_e32 v153, v131
	v_mov_b32_e32 v155, v132
	v_mov_b32_e32 v165, v135
	v_mov_b32_e32 v166, v137
	v_mov_b32_e32 v160, v139
	v_mov_b32_e32 v162, v141
	v_mov_b32_e32 v170, v143
	v_mov_b32_e32 v171, v145
	v_mov_b32_e32 v167, v147
	v_mov_b32_e32 v169, v148
	s_waitcnt vmcnt(0)
	v_mul_f32_e32 v42, v214, v44
	v_lshlrev_b32_e32 v44, 16, v54
	v_mul_f32_e32 v36, v215, v36
	v_and_b32_e32 v43, 0xffff0000, v54
	v_mul_f32_e32 v42, v42, v44
	v_mul_f32_e32 v36, v36, v43
	v_cvt_pk_bf16_f32 v36, v42, v36
	v_lshlrev_b32_e32 v44, 16, v37
	v_and_b32_e32 v37, 0xffff0000, v37
	v_mul_f32_e32 v42, v216, v44
	v_lshlrev_b32_e32 v44, 16, v55
	v_mul_f32_e32 v37, v217, v37
	v_and_b32_e32 v43, 0xffff0000, v55
	v_mul_f32_e32 v42, v42, v44
	v_mul_f32_e32 v37, v37, v43
	v_cvt_pk_bf16_f32 v37, v42, v37
	v_lshlrev_b32_e32 v44, 16, v38
	v_and_b32_e32 v38, 0xffff0000, v38
	v_mul_f32_e32 v42, v218, v44
	v_lshlrev_b32_e32 v44, 16, v56
	v_mul_f32_e32 v38, v219, v38
	v_and_b32_e32 v43, 0xffff0000, v56
	v_mul_f32_e32 v42, v42, v44
	v_mul_f32_e32 v38, v38, v43
	v_cvt_pk_bf16_f32 v38, v42, v38
	v_lshlrev_b32_e32 v44, 16, v39
	v_and_b32_e32 v39, 0xffff0000, v39
	v_mul_f32_e32 v39, v221, v39
	v_and_b32_e32 v43, 0xffff0000, v57
	v_mul_f32_e32 v42, v220, v44
	v_lshlrev_b32_e32 v44, 16, v57
	v_mul_f32_e32 v39, v39, v43
	v_mul_f32_e32 v42, v42, v44
	v_cvt_pk_bf16_f32 v39, v42, v39
	global_store_dwordx4 v[40:41], v[36:39], off offset:2048
	s_nop 1
	ds_read_b128 v[36:39], v107 offset:16
	v_mov_b64_e32 v[54:55], v[58:59]
	v_mov_b32_e32 v43, v112
	v_mov_b32_e32 v44, v115
	v_mov_b64_e32 v[56:57], v[60:61]
	s_waitcnt lgkmcnt(0)
	v_lshlrev_b32_e32 v42, 16, v36
	v_and_b32_e32 v36, 0xffff0000, v36
	v_mul_f32_e32 v40, v222, v42
	v_lshlrev_b32_e32 v42, 16, v50
	v_mul_f32_e32 v36, v223, v36
	v_and_b32_e32 v41, 0xffff0000, v50
	v_mul_f32_e32 v40, v40, v42
	v_mul_f32_e32 v36, v36, v41
	v_cvt_pk_bf16_f32 v36, v40, v36
	v_lshlrev_b32_e32 v42, 16, v37
	v_and_b32_e32 v37, 0xffff0000, v37
	v_mul_f32_e32 v40, v224, v42
	v_lshlrev_b32_e32 v42, 16, v51
	v_mul_f32_e32 v37, v225, v37
	v_and_b32_e32 v41, 0xffff0000, v51
	v_mul_f32_e32 v40, v40, v42
	v_mul_f32_e32 v37, v37, v41
	v_cvt_pk_bf16_f32 v37, v40, v37
	v_lshlrev_b32_e32 v42, 16, v38
	v_and_b32_e32 v38, 0xffff0000, v38
	v_mul_f32_e32 v40, v226, v42
	v_lshlrev_b32_e32 v42, 16, v52
	v_mul_f32_e32 v38, v227, v38
	v_and_b32_e32 v41, 0xffff0000, v52
	v_mul_f32_e32 v40, v40, v42
	v_mul_f32_e32 v38, v38, v41
	v_cvt_pk_bf16_f32 v38, v40, v38
	v_lshlrev_b32_e32 v42, 16, v39
	v_and_b32_e32 v39, 0xffff0000, v39
	v_mul_f32_e32 v39, v229, v39
	v_and_b32_e32 v41, 0xffff0000, v53
	v_mul_f32_e32 v40, v228, v42
	v_lshlrev_b32_e32 v42, 16, v53
	v_mul_f32_e32 v39, v39, v41
	v_mul_f32_e32 v40, v40, v42
	v_cvt_pk_bf16_f32 v39, v40, v39
	v_mov_b64_e32 v[50:51], v[62:63]
	global_store_dwordx4 v[34:35], v[36:39], off offset:16
	v_mov_b32_e32 v40, v120
	v_mov_b32_e32 v41, v121
	v_mov_b32_e32 v37, v122
	v_mov_b32_e32 v36, v119
	v_mov_b32_e32 v39, v116
	v_mov_b32_e32 v38, v113
	v_mov_b64_e32 v[52:53], v[64:65]
	s_cbranch_scc0 .LBB0_235
; DI float bf2f(unsigned b) { return __uint_as_float(b << 16); }
; DI void hgrn2_block(const Args& a, unsigned char* lds, int bh, int tid, int wave, int lane) {
;     ...
;         for (int j = 0; j < 16; ++j) { fq_[j] = bf2f(pq[j]); const float g = bf2f(pg[j]); ff[j] = 1.f - __expf(g); run += g; cum[j] = run;
;             if (j & 1) vw[j >> 1] |= (unsigned)pv[j] << 16; else vw[j >> 1] = pv[j]; }
;         seg[tq * 128 + k] = run;
;         if (c + 1 < 32) {
;             const bf16_t* base = Y1 + (size_t)(tok0 + 64 * (c + 1) + 16 * tq) * NY1 + h * 128 + k;
; #pragma unroll
;             for (int j = 0; j < 16; ++j) { pq[j] = base[(size_t)j * NY1 + 2048]; pg[j] = base[(size_t)j * NY1 + 3072]; pv[j] = base[(size_t)j * NY1 + 4096]; }
;             const u32x4* hgp = (const u32x4*)(Y1 + (size_t)(tok0 + 64 * (c + 1) + (tid >> 3)) * NY1 + 5120 + h * 128 + (tid & 7) * 16); phg[0] = hgp[0]; phg[1] = hgp[1]; }
.LBB0_227:
	v_lshlrev_b32_e32 v202, 16, v73
	v_add_f32_e32 v42, 0, v202
	v_lshlrev_b32_e32 v201, 16, v74
	v_add_f32_e32 v186, v42, v201
	v_lshlrev_b32_e32 v200, 16, v75
	v_add_f32_e32 v185, v186, v200
	v_lshlrev_b32_e32 v199, 16, v76
	v_add_f32_e32 v184, v185, v199
	v_lshlrev_b32_e32 v198, 16, v77
	v_add_f32_e32 v183, v184, v198
	v_lshlrev_b32_e32 v197, 16, v79
	v_add_f32_e32 v182, v183, v197
	v_lshlrev_b32_e32 v196, 16, v82
	v_add_f32_e32 v181, v182, v196
	v_lshlrev_b32_e32 v195, 16, v89
	v_add_f32_e32 v180, v181, v195
	v_lshlrev_b32_e32 v194, 16, v110
	v_add_f32_e32 v179, v180, v194
	v_lshlrev_b32_e32 v193, 16, v111
	v_add_f32_e32 v178, v179, v193
	v_lshlrev_b32_e32 v192, 16, v114
	v_add_f32_e32 v177, v178, v192
	v_lshlrev_b32_e32 v191, 16, v117
	v_add_f32_e32 v176, v177, v191
	v_lshlrev_b32_e32 v190, 16, v118
	v_add_f32_e32 v175, v176, v190
	v_lshlrev_b32_e32 v189, 16, v123
	v_add_f32_e32 v174, v175, v189
	v_lshlrev_b32_e32 v188, 16, v126
	v_add_f32_e32 v173, v174, v188
	v_lshlrev_b32_e32 v187, 16, v127
	v_add_f32_e32 v172, v173, v187
	s_cmpk_eq_i32 s87, 0x7c0
	ds_write_b32 v80, v172
	s_cbranch_scc1 .LBB0_229
	v_add_u32_e32 v34, s87, v102
	v_mad_i64_i32 v[34:35], s[68:69], v34, s72, v[68:69]
	s_mov_b64 s[98:99], 0x3000
	v_add_co_u32_e32 v58, vcc, 0x1800, v34
	s_nop 1
	v_addc_co_u32_e32 v59, vcc, 0, v35, vcc
	global_load_ushort v112, v[58:59], off offset:-2048
	global_load_ushort v73, v[58:59], off
	global_load_ushort v113, v[58:59], off offset:2048
	v_lshl_add_u64 v[58:59], v[58:59], 0, s[98:99]
	global_load_ushort v115, v[58:59], off offset:-2048
	global_load_ushort v74, v[58:59], off
	global_load_ushort v116, v[58:59], off offset:2048
	v_lshl_add_u64 v[58:59], v[58:59], 0, s[98:99]
	global_load_ushort v120, v[58:59], off offset:-2048
	global_load_ushort v75, v[58:59], off
	global_load_ushort v119, v[58:59], off offset:2048
	v_lshl_add_u64 v[58:59], v[58:59], 0, s[98:99]
	global_load_ushort v121, v[58:59], off offset:-2048
	global_load_ushort v76, v[58:59], off
	global_load_ushort v122, v[58:59], off offset:2048
	v_lshl_add_u64 v[58:59], v[58:59], 0, s[98:99]
	global_load_ushort v124, v[58:59], off offset:-2048
	global_load_ushort v77, v[58:59], off
	global_load_ushort v125, v[58:59], off offset:2048
	v_lshl_add_u64 v[58:59], v[58:59], 0, s[98:99]
	global_load_ushort v129, v[58:59], off offset:-2048
	global_load_ushort v79, v[58:59], off
	global_load_ushort v128, v[58:59], off offset:2048
	v_lshl_add_u64 v[58:59], v[58:59], 0, s[98:99]
	global_load_ushort v131, v[58:59], off offset:-2048
	global_load_ushort v82, v[58:59], off
	global_load_ushort v130, v[58:59], off offset:2048
	v_lshl_add_u64 v[58:59], v[58:59], 0, s[98:99]
	global_load_ushort v132, v[58:59], off offset:-2048
	global_load_ushort v89, v[58:59], off
	global_load_ushort v133, v[58:59], off offset:2048
	v_lshl_add_u64 v[58:59], v[58:59], 0, s[98:99]
	global_load_ushort v135, v[58:59], off offset:-2048
	global_load_ushort v110, v[58:59], off
	global_load_ushort v134, v[58:59], off offset:2048
	v_lshl_add_u64 v[58:59], v[58:59], 0, s[98:99]
	global_load_ushort v137, v[58:59], off offset:-2048
	global_load_ushort v111, v[58:59], off
	global_load_ushort v136, v[58:59], off offset:2048
	v_lshl_add_u64 v[58:59], v[58:59], 0, s[98:99]
	global_load_ushort v139, v[58:59], off offset:-2048
	global_load_ushort v114, v[58:59], off
	global_load_ushort v138, v[58:59], off offset:2048
	v_lshl_add_u64 v[58:59], v[58:59], 0, s[98:99]
	global_load_ushort v141, v[58:59], off offset:-2048
	global_load_ushort v117, v[58:59], off
	global_load_ushort v140, v[58:59], off offset:2048
	v_lshl_add_u64 v[58:59], v[58:59], 0, s[98:99]
	global_load_ushort v143, v[58:59], off offset:-2048
	global_load_ushort v118, v[58:59], off
	global_load_ushort v142, v[58:59], off offset:2048
	v_lshl_add_u64 v[58:59], v[58:59], 0, s[98:99]
	global_load_ushort v145, v[58:59], off offset:-2048
	global_load_ushort v123, v[58:59], off
	global_load_ushort v144, v[58:59], off offset:2048
	v_lshl_add_u64 v[58:59], v[58:59], 0, s[98:99]
	global_load_ushort v147, v[58:59], off offset:-2048
	global_load_ushort v126, v[58:59], off
	global_load_ushort v146, v[58:59], off offset:2048
	v_lshl_add_u64 v[58:59], v[58:59], 0, s[98:99]
	global_load_ushort v148, v[58:59], off offset:-2048
	global_load_ushort v127, v[58:59], off
	global_load_ushort v149, v[58:59], off offset:2048
	v_add3_u32 v58, v78, s87, 64
	v_mov_b64_e32 v[34:35], s[90:91]
	v_mad_i64_i32 v[34:35], s[68:69], v58, s72, v[34:35]
	v_lshl_add_u64 v[34:35], v[34:35], 0, s[92:93]
	v_lshl_add_u64 v[34:35], v[34:35], 0, v[66:67]
	v_lshl_add_u64 v[62:63], v[34:35], 0, s[94:95]
	v_add_co_u32_e32 v34, vcc, 0x2000, v34
	s_nop 1
	v_addc_co_u32_e32 v35, vcc, 0, v35, vcc
	global_load_dwordx4 v[58:61], v[34:35], off offset:2048
	s_nop 0
	global_load_dwordx4 v[62:65], v[62:63], off offset:16

; __global__ void __launch_bounds__(NTHR) fwd_kernel(Args a_k) {
	.amdhsa_kernel _Z10fwd_kernel4Args
		.amdhsa_group_segment_fixed_size 0
		.amdhsa_private_segment_fixed_size 0
		.amdhsa_kernarg_size 472
		.amdhsa_user_sgpr_count 2
		.amdhsa_user_sgpr_dispatch_ptr 0
		.amdhsa_user_sgpr_queue_ptr 0
		.amdhsa_user_sgpr_kernarg_segment_ptr 1
		.amdhsa_user_sgpr_dispatch_id 0
		.amdhsa_user_sgpr_kernarg_preload_length 0
		.amdhsa_user_sgpr_kernarg_preload_offset 0
		.amdhsa_user_sgpr_private_segment_size 0
		.amdhsa_uses_dynamic_stack 0
		.amdhsa_enable_private_segment 0
		.amdhsa_system_sgpr_workgroup_id_x 1
		.amdhsa_system_sgpr_workgroup_id_y 0
		.amdhsa_system_sgpr_workgroup_id_z 0
		.amdhsa_system_sgpr_workgroup_info 0
		.amdhsa_system_vgpr_workitem_id 2
		.amdhsa_next_free_vgpr 255
		.amdhsa_next_free_sgpr 100
		.amdhsa_accum_offset 256
		.amdhsa_reserve_vcc 1
		.amdhsa_float_round_mode_32 0
		.amdhsa_float_round_mode_16_64 0
		.amdhsa_float_denorm_mode_32 3
		.amdhsa_float_denorm_mode_16_64 3
		.amdhsa_dx10_clamp 1
		.amdhsa_ieee_mode 1
		.amdhsa_fp16_overflow 0
		.amdhsa_tg_split 0
		.amdhsa_exception_fp_ieee_invalid_op 0
		.amdhsa_exception_fp_denorm_src 0
		.amdhsa_exception_fp_ieee_div_zero 0
		.amdhsa_exception_fp_ieee_overflow 0
		.amdhsa_exception_fp_ieee_underflow 0
		.amdhsa_exception_fp_ieee_inexact 0
		.amdhsa_exception_int_div_zero 0
	.end_amdhsa_kernel

; __global__ void __launch_bounds__(NTHR) fwd_kernel(Args a_k) {
amdhsa.kernels:
  - .agpr_count:     0
    .args:
      - .offset:         0
        .size:           216
        .value_kind:     by_value
      - .offset:         216
        .size:           4
        .value_kind:     hidden_block_count_x
      - .offset:         220
        .size:           4
        .value_kind:     hidden_block_count_y
      - .offset:         224
        .size:           4
        .value_kind:     hidden_block_count_z
      - .offset:         228
        .size:           2
        .value_kind:     hidden_group_size_x
      - .offset:         230
        .size:           2
        .value_kind:     hidden_group_size_y
      - .offset:         232
        .size:           2
        .value_kind:     hidden_group_size_z
      - .offset:         234
        .size:           2
        .value_kind:     hidden_remainder_x
      - .offset:         236
        .size:           2
        .value_kind:     hidden_remainder_y
      - .offset:         238
        .size:           2
        .value_kind:     hidden_remainder_z
      - .offset:         256
        .size:           8
        .value_kind:     hidden_global_offset_x
      - .offset:         264
        .size:           8
        .value_kind:     hidden_global_offset_y
      - .offset:         272
        .size:           8
        .value_kind:     hidden_global_offset_z
      - .offset:         280
        .size:           2
        .value_kind:     hidden_grid_dims
      - .offset:         304
        .size:           8
        .value_kind:     hidden_multigrid_sync_arg
      - .offset:         336
        .size:           4
        .value_kind:     hidden_dynamic_lds_size
    .group_segment_fixed_size: 0
    .kernarg_segment_align: 8
    .kernarg_segment_size: 472
    .language:       OpenCL C
    .language_version:
      - 2
      - 0
    .max_flat_workgroup_size: 512
    .name:           _Z10fwd_kernel4Args
    .private_segment_fixed_size: 0
    .sgpr_count:     106
    .sgpr_spill_count: 8
    .symbol:         _Z10fwd_kernel4Args.kd
    .uniform_work_group_size: 1
    .uses_dynamic_stack: false
    .vgpr_count:     255
    .vgpr_spill_count: 0
    .wavefront_size: 64
